# grid barrier: XCD leader bumps the local generation before its own acquire (one round trip less on the release path)
# baseline (speedup 1.0000x reference)
.LBB0_215:
	s_waitcnt vmcnt(0)
	buffer_inv sc1
	s_waitcnt vmcnt(0)
	buffer_inv sc1
	s_lshl_b32 s0, s74, 3
	s_or_b32 s2, s0, 1
	v_readlane_b32 s4, v254, 3
	v_readlane_b32 s5, v254, 4
	s_cmp_le_i32 s4, s2
	v_writelane_b32 v255, s0, 26
	s_cselect_b64 s[0:1], -1, 0
	s_cmp_lt_i32 s2, s5
	s_cselect_b64 s[2:3], -1, 0
	s_and_b64 s[0:1], s[0:1], s[2:3]
	s_andn2_b64 vcc, exec, s[0:1]
	s_cbranch_vccnz .LBB0_316
	s_mov_b32 s0, s23
	s_getreg_b32 s1, hwreg(HW_REG_HW_ID, 0, 6)
	v_readlane_b32 s15, v254, 2
	s_mov_b32 s1, s92
	v_mbcnt_lo_u32_b32 v0, -1, 0
	v_mbcnt_hi_u32_b32 v0, -1, v0
	s_ashr_i32 s1, s0, 31
	s_lshl_b64 s[0:1], s[0:1], 3
	v_readlane_b32 s2, v254, 0
	v_readlane_b32 s3, v254, 1
	s_add_u32 s2, s2, s0
	s_addc_u32 s3, s3, s1
	s_mov_b32 s19, s92
	s_load_dwordx2 s[0:1], s[2:3], 0x88
	s_lshl_b32 s22, s74, 2
	s_lshl_b64 s[4:5], s[22:23], 2
	s_waitcnt lgkmcnt(0)
	s_add_u32 s0, s0, s4
	s_addc_u32 s1, s1, s5
	global_load_dwordx4 v[2:5], v1, s[0:1]
	s_getreg_b32 s0, hwreg(HW_REG_HW_ID, 0, 6)
	s_and_b32 s0, s0, 63
	s_lshl_b32 s0, s0, 2
	s_add_i32 s0, s0, 0
	s_add_i32 s0, s0, 0x20400
	v_mov_b32_e32 v0, s0
	ds_read_b32 v0, v0
	s_cmpk_lt_i32 s19, 0x2cb
	s_cselect_b64 s[8:9], -1, 0
	s_cmpk_gt_i32 s19, 0x2ca
	s_waitcnt lgkmcnt(0)
	v_readfirstlane_b32 s0, v0
	v_mbcnt_lo_u32_b32 v0, -1, 0
	v_mbcnt_hi_u32_b32 v0, -1, v0
	s_nop 1
	v_lshl_add_u32 v6, s0, 6, v0
	s_nop 0
	v_readfirstlane_b32 s0, v6
	s_cbranch_scc1 .LBB0_222
	s_ashr_i32 s1, s19, 31
	s_lshr_b32 s1, s1, 29
	s_add_i32 s1, s19, s1
	s_and_b32 s4, s1, -8
	s_sub_i32 s6, s19, s4
	s_cmp_gt_i32 s6, 2
	s_mov_b64 s[4:5], -1
	s_cbranch_scc0 .LBB0_219
	s_mul_i32 s4, s6, 0x59
	s_add_i32 s7, s4, 3
	s_mov_b64 s[4:5], 0

.LBB0_312:
	s_or_b64 exec, exec, s[4:5]
	s_mov_b64 s[4:5], exec
	v_mbcnt_lo_u32_b32 v0, s4, 0
	v_mbcnt_hi_u32_b32 v0, s5, v0
	v_cmp_eq_u32_e32 vcc, 0, v0
	s_and_saveexec_b64 s[6:7], vcc
	s_cbranch_execz .LBB0_314
	s_bcnt1_i32_b64 s0, s[4:5]
	v_mov_b32_e32 v0, s0
	v_readlane_b32 s0, v255, 9
	v_readlane_b32 s1, v255, 10
	s_nop 4
	global_atomic_add v1, v0, s[0:1]
.LBB0_314:
	s_or_b64 exec, exec, s[6:7]
	s_waitcnt vmcnt(0)
	buffer_inv sc1
	s_waitcnt vmcnt(0)
.LBB0_315:
	s_or_b64 exec, exec, s[2:3]
	s_waitcnt lgkmcnt(0)
	s_barrier

.LBB0_543:
	s_waitcnt vmcnt(0)
	buffer_inv sc1
	v_readlane_b32 s0, v255, 26
	s_or_b32 s2, s0, 3
	v_readlane_b32 s4, v254, 3
	v_readlane_b32 s5, v254, 4
	s_cmp_le_i32 s4, s2
	s_cselect_b64 s[0:1], -1, 0
	s_cmp_lt_i32 s2, s5
	s_cselect_b64 s[2:3], -1, 0
	s_and_b64 s[0:1], s[0:1], s[2:3]
	s_andn2_b64 vcc, exec, s[0:1]
	s_cbranch_vccnz .LBB0_840
	s_mov_b32 s2, s23
	s_getreg_b32 s0, hwreg(HW_REG_HW_ID, 0, 6)
	v_readlane_b32 s15, v254, 2
	v_mbcnt_lo_u32_b32 v0, -1, 0
	v_mbcnt_hi_u32_b32 v0, -1, v0
	s_and_b32 s0, s15, 7
	s_mov_b32 s19, s92
	s_cmp_lg_u32 s0, 0
	s_cbranch_scc0 .LBB0_546
	s_cmpk_gt_i32 s19, 0xff
	s_cbranch_scc0 .LBB0_547
	s_branch .LBB0_629

.LBB0_840:
	s_waitcnt vmcnt(0)
	buffer_inv sc1
	v_readlane_b32 s0, v255, 26
	s_or_b32 s2, s0, 4
	v_readlane_b32 s4, v254, 3
	v_readlane_b32 s5, v254, 4
	s_cmp_le_i32 s4, s2
	s_cselect_b64 s[0:1], -1, 0
	s_cmp_lt_i32 s2, s5
	s_cselect_b64 s[2:3], -1, 0
	s_and_b64 s[0:1], s[0:1], s[2:3]
	s_andn2_b64 vcc, exec, s[0:1]
	s_cbranch_vccnz .LBB0_961
	s_mov_b32 s0, s23
	s_getreg_b32 s1, hwreg(HW_REG_HW_ID, 0, 6)
	v_readlane_b32 s45, v254, 2
	s_mov_b32 s1, s92
	v_mbcnt_lo_u32_b32 v0, -1, 0
	v_mbcnt_hi_u32_b32 v0, -1, v0
	s_ashr_i32 s1, s0, 31
	s_lshl_b64 s[0:1], s[0:1], 3
	v_readlane_b32 s2, v254, 0
	v_readlane_b32 s3, v254, 1
	s_add_u32 s0, s2, s0
	s_addc_u32 s1, s3, s1
	s_load_dwordx2 s[8:9], s[0:1], 0x100
	s_mov_b64 s[2:3], -1
	s_waitcnt lgkmcnt(0)
	s_add_u32 s22, s8, 0x10f60000
	s_addc_u32 s44, s9, 0
	s_lshl_b32 s0, s74, 21
	s_add_u32 s0, s8, s0
	s_addc_u32 s1, s9, 0
	s_add_u32 s15, s0, 0xd00000
	s_addc_u32 s19, s1, 0
	s_add_u32 s4, s8, 0x9580000
	s_addc_u32 s5, s9, 0
	s_add_u32 s6, s8, 0x12fe0000
	s_addc_u32 s7, s9, 0
	s_cmpk_lg_i32 s45, 0x100
	s_cbranch_scc0 .LBB0_883
	s_mov_b32 s46, s92
	s_getreg_b32 s0, hwreg(HW_REG_HW_ID, 0, 6)
	s_and_b32 s0, s0, 63
	s_lshl_b32 s0, s0, 2
	s_add_i32 s0, s0, 0
	s_add_i32 s0, s0, 0x20400
	v_mov_b32_e32 v0, s0
	ds_read_b32 v0, v0
	v_mbcnt_lo_u32_b32 v16, -1, 0
	v_mbcnt_hi_u32_b32 v16, -1, v16
	s_cmpk_gt_i32 s46, 0xff
	s_waitcnt lgkmcnt(0)
	v_readfirstlane_b32 s0, v0
	s_nop 1
	v_lshl_add_u32 v0, s0, 6, v16
	s_nop 0
	v_readfirstlane_b32 s1, v0
	s_cbranch_scc1 .LBB0_866
	s_ashr_i32 s47, s46, 31
	s_lshr_b32 s0, s47, 29
	s_add_i32 s11, s46, s0
	s_and_b32 s0, s11, -8
	s_sub_i32 s10, s46, s0
	s_cmp_gt_i32 s10, -1
	s_cbranch_scc0 .LBB0_845
	s_lshl_b32 s0, s10, 5
	s_mov_b64 s[2:3], 0

.LBB0_959:
	s_or_b64 exec, exec, s[6:7]
	s_waitcnt vmcnt(0)
	buffer_inv sc1
	s_waitcnt vmcnt(0)
.LBB0_960:
	s_or_b64 exec, exec, s[2:3]
	s_waitcnt lgkmcnt(0)
	s_barrier

.LBB0_1025:
	s_or_b64 exec, exec, s[6:7]
	s_waitcnt vmcnt(0)
	buffer_inv sc1
	s_waitcnt vmcnt(0)
.LBB0_1026:
	s_or_b64 exec, exec, s[2:3]
	s_waitcnt lgkmcnt(0)
	s_barrier

.LBB0_1457:
	s_waitcnt vmcnt(0)
	buffer_inv sc1
	v_readlane_b32 s0, v255, 26
	s_or_b32 s2, s0, 7
	v_readlane_b32 s4, v254, 3
	v_readlane_b32 s5, v254, 4
	s_cmp_le_i32 s4, s2
	s_cselect_b64 s[0:1], -1, 0
	s_cmp_lt_i32 s2, s5
	s_cselect_b64 s[2:3], -1, 0
	s_and_b64 s[0:1], s[0:1], s[2:3]
	s_andn2_b64 vcc, exec, s[0:1]
	s_cbranch_vccnz .LBB0_1599
	s_mov_b32 s0, s23
	s_getreg_b32 s1, hwreg(HW_REG_HW_ID, 0, 6)
	s_and_b32 s1, s1, 63
	s_lshl_b32 s1, s1, 2
	s_add_i32 s1, s1, 0
	s_add_i32 s1, s1, 0x20400
	v_mov_b32_e32 v0, s1
	ds_read_b32 v0, v0
	v_readlane_b32 s15, v254, 2
	v_mbcnt_lo_u32_b32 v2, -1, 0
	v_mbcnt_hi_u32_b32 v2, -1, v2
	v_readlane_b32 s2, v254, 0
	s_waitcnt lgkmcnt(0)
	v_readfirstlane_b32 s1, v0
	v_readlane_b32 s3, v254, 1
	s_mov_b32 s16, s92
	v_lshl_add_u32 v0, s1, 6, v2
	s_mov_b32 s1, s92
	s_ashr_i32 s1, s0, 31
	s_lshl_b64 s[0:1], s[0:1], 3
	s_add_u32 s2, s2, s0
	s_addc_u32 s3, s3, s1
	s_load_dwordx2 s[4:5], s[2:3], 0x100
	s_movk_i32 s0, 0x150
	s_ashr_i32 s17, s16, 31
	v_cmp_gt_i32_e64 s[36:37], s0, v0
	v_lshlrev_b32_e32 v82, 3, v0
	s_mul_i32 s22, s74, 0x1f80
	s_mul_i32 s0, s74, 0xa80
	s_mov_b32 s1, s23
	s_ashr_i32 s46, s15, 31
	v_ashrrev_i32_e32 v83, 31, v82
	s_lshl_b64 s[6:7], s[22:23], 2
	s_lshl_b64 s[10:11], s[0:1], 2
	s_mov_b64 s[12:13], s[16:17]
	v_readlane_b32 s22, v255, 35
	s_branch .LBB0_1462

.LBB0_1597:
	s_or_b64 exec, exec, s[6:7]
	s_waitcnt vmcnt(0)
	buffer_inv sc1
	s_waitcnt vmcnt(0)
.LBB0_1598:
	s_or_b64 exec, exec, s[2:3]
	s_waitcnt lgkmcnt(0)
	s_barrier

.LBB0_1698:
	s_or_b64 exec, exec, s[4:5]
	s_mov_b64 s[4:5], exec
	v_mbcnt_lo_u32_b32 v0, s4, 0
	v_mbcnt_hi_u32_b32 v0, s5, v0
	v_cmp_eq_u32_e32 vcc, 0, v0
	s_and_saveexec_b64 s[6:7], vcc
	s_cbranch_execnz .LBB0_1699
	s_getpc_b64 s[98:99]
